# MLA phase: static s_setprio 1 for waves 4-7 (natural half-step stagger of the two waves per SIMD), reset at phase end
# baseline (speedup 1.0000x reference)
; __global__ void __launch_bounds__(NTHR, 2) mk_fwd(Args a) {
;     ...
;                 for (int i = 0; i < 4; ++i) {
;                     const int xg = bid & 7, li = bid >> 3, h = li >> 2, p = li & 3;
;                     const int b = 2 * xg + (i >> 1); const int qb = (i & 1) ? p : 7 - p;
;                     const size_t rb = (size_t)b * 2048;
;                     att::attn_unit<96, 0>(QM + rb * 768 + h * 96, 768, KM + rb * 768 + h * 96, 768, VM + rb * 512 + h * 64, 512, O0 + rb * 1024 + 512 + h * 64, 1024, qb, (char*)lds,
;                                           0.10206207261596575f * att::kLog2e);
;                 }
;                 __syncthreads();
.LBB0_1349:
	s_add_i32 s0, s7, -1
	s_cmp_lt_i32 s7, 2
	s_mov_b32 s7, s0
	s_setprio 0
	s_barrier
	s_cbranch_scc1 .LBB0_1376
.LBB0_1350:
	v_readfirstlane_b32 s8, v238
	s_nop 3
	s_cmp_ge_u32 s8, 0x100
	s_cbranch_scc0 .Lmla_prio_lo
	s_setprio 1
